# v69 + MoBA attention: waves 0-3 run at issue priority 2, waves 4-7 at 0 (the two waves of a SIMD drift apart so LDS/MFMA stages overlap the partner's softmax stage)
# baseline (speedup 1.0000x reference)
; __device__ __forceinline__ void lds_barrier() { asm volatile("s_waitcnt lgkmcnt(0)" ::: "memory"); __builtin_amdgcn_s_barrier(); asm volatile("" ::: "memory"); }
; __global__ void __launch_bounds__(NTHREADS, 2) mega(Args a) {
;     ...
;         for (int qo = 0; qo < 8; ++qo) {
;             const int qx = (int)((xcc + (unsigned)qo) & 7u);
;             for (;;) {
;                 lds_barrier();
;                 if (tidA == 0) *uslot = atomicAdd(cnt + qx, 1u);
;                 lds_barrier();
;                 const int k = (int)*uslot;
;                 if (k >= 128 || (a.probe & 16)) break;
;                 const int qt = 31 - (k & 31), bh = qx + 8 * (k >> 5), b = bh >> 3, h = bh & 7;
;                 const bf16_t* base = proj + (size_t)(b * SEQ) * NIN + h * 128;
;                 attn_unit<true>(lds, base + (size_t)(qt * 128) * NIN, NIN, base + 1024, base + 2048, NIN, proj + (size_t)(b * SEQ + qt * 128) * NIN + h * 128, NIN, qt,
;                                 (const float*)(ws + WS_KMEAN) + (size_t)bh * 8192, AIN(I_RELB) + h, tidA);
.LBB0_1138:
	v_readfirstlane_b32 s32, v205
	s_cmpk_lt_u32 s32, 0x100
	s_cbranch_scc0 .Lprio_skip
	s_setprio 2

; __device__ __forceinline__ unsigned xb_add(unsigned* p, unsigned v) { return __hip_atomic_fetch_add(p, v, __ATOMIC_RELAXED, __HIP_MEMORY_SCOPE_AGENT); }
; __device__ __forceinline__ void xcd_barrier(const XcdBarrier& b) {
;     asm volatile("s_waitcnt vmcnt(0)" ::: "memory");
;     __syncthreads();
;     if (threadIdx.x == 0) {
;         unsigned* bar = b.bar;
;         __builtin_amdgcn_s_waitcnt(0);
;         unsigned nloc = b.st[0], nx = b.st[1];
;         if (nloc == 0u) { xcd_barrier_complete(bar, b.x, nloc, nx); b.st[0] = nloc; b.st[1] = nx; }
;         const unsigned old = xb_add(&bar[XB_XSUB(b.x)], 1u);
.LBB0_1259:
	s_cmp_gt_i32 s65, 6
	s_cselect_b64 s[0:1], -1, 0
	s_and_b64 s[2:3], s[12:13], s[0:1]
	s_andn2_b64 vcc, exec, s[2:3]
	s_cbranch_vccnz .LBB0_1327
	s_cmpk_lt_u32 s65, 0x3e9
	s_mov_b64 s[4:5], -1
	s_cbranch_scc0 .LBB0_1314
	s_setprio 0
	s_waitcnt vmcnt(0)
	s_waitcnt lgkmcnt(0)
	s_barrier
	s_mov_b64 s[4:5], exec
	v_readlane_b32 s2, v253, 9
	v_readlane_b32 s3, v253, 10
	s_and_b64 s[2:3], s[4:5], s[2:3]
	s_mov_b64 exec, s[2:3]
	s_cbranch_execz .LBB0_1313
	s_add_i32 s2, 0, 0x27500
	v_mov_b32_e32 v0, s2
	s_waitcnt vmcnt(0) expcnt(0) lgkmcnt(0)
	ds_read_b32 v2, v0
	s_add_i32 s2, 0, 0x27504
	v_mov_b32_e32 v0, s2
	ds_read_b32 v0, v0
	s_waitcnt lgkmcnt(1)
	v_cmp_ne_u32_e32 vcc, 0, v2
	s_cbranch_vccnz .LBB0_1277
	v_readlane_b32 s6, v253, 2
	v_readlane_b32 s7, v253, 3
	v_readlane_b32 s12, v253, 6
	s_load_dwordx2 s[2:3], s[6:7], 0x4
	v_readlane_b32 s13, v253, 7
	s_add_u32 s6, s12, 0x1000
	s_addc_u32 s7, s13, 0
	s_add_u32 s8, s12, 0x1100
	s_addc_u32 s9, s13, 0
	s_add_u32 s10, s12, 0x1200
	s_addc_u32 s11, s13, 0
	s_waitcnt lgkmcnt(0)
	s_mul_i32 s2, s2, s69
	s_add_u32 s12, s12, 0x1300
	s_mul_i32 s2, s2, s3
	s_addc_u32 s13, s13, 0
	s_mov_b32 s3, 1
	v_mov_b32_e32 v16, 0
	s_branch .LBB0_1265
